# grid barrier: the mid-arriving workgroup of each XCD starts an L2 write-back before polling, so the leader's write-back at the end has less left to flush
# speedup vs baseline: 1.0114x; 1.0114x over previous
.LBB0_471:
	s_lshl_b32 s24, s38, 6
	s_add_i32 s54, s24, 0x500
	s_lshl_b64 s[4:5], s[54:55], 2
	s_add_u32 s4, s2, s4
	s_addc_u32 s5, s3, s5
	v_mov_b64_e32 v[6:7], s[4:5]
	flat_atomic_add v6, v[6:7], v215 sc0
	v_cvt_f32_u32_e32 v5, v4
	v_sub_u32_e32 v7, 0, v4
	v_rcp_iflag_f32_e32 v5, v5
	s_nop 0
	v_mul_f32_e32 v5, 0x4f7ffffe, v5
	v_cvt_u32_f32_e32 v5, v5
	v_mul_lo_u32 v7, v7, v5
	v_mul_hi_u32 v7, v5, v7
	v_add_u32_e32 v5, v5, v7
	s_waitcnt vmcnt(0) lgkmcnt(0)
	v_mul_hi_u32 v5, v6, v5
	v_mul_lo_u32 v7, v5, v4
	v_sub_u32_e32 v7, v6, v7
	v_cmp_ge_u32_e32 vcc, v7, v4
	v_add_u32_e32 v8, 1, v5
	s_nop 0
	v_cndmask_b32_e32 v5, v5, v8, vcc
	v_sub_u32_e32 v8, v7, v4
	v_cndmask_b32_e32 v7, v7, v8, vcc
	v_cmp_ge_u32_e32 vcc, v7, v4
	v_add_u32_e32 v7, 1, v5
	v_add_u32_e32 v8, 1, v6
	v_cndmask_b32_e32 v5, v5, v7, vcc
	v_mad_u64_u32 v[6:7], s[4:5], v4, v5, v[4:5]
	v_cmp_ne_u32_e32 vcc, v8, v6
	s_and_saveexec_b64 s[4:5], vcc
	s_xor_b64 s[4:5], exec, s[4:5]
	s_cbranch_execz .LBB0_484
	v_and_b32_e32 v2, 15, v8
	v_cmp_ne_u32_e32 vcc, 0, v2
	s_cbranch_vccnz .Lewb_0
	buffer_wbl2 sc1
.Lewb_0:
	s_add_i32 s54, s24, 0x900
	s_lshl_b64 s[6:7], s[54:55], 2
	s_add_u32 s8, s2, s6
	s_addc_u32 s9, s3, s7
	v_mov_b64_e32 v[6:7], s[8:9]
	flat_load_dword v2, v[6:7] sc1
	s_waitcnt vmcnt(0) lgkmcnt(0)
	v_cmp_eq_u32_e32 vcc, v2, v5
	s_and_saveexec_b64 s[6:7], vcc
	s_cbranch_execz .LBB0_483
	s_mov_b32 s25, 1
	s_mov_b64 s[10:11], 0
	s_branch .LBB0_475

.LBB0_809:
	s_lshl_b32 s26, s41, 6
	s_add_i32 s54, s26, 0x500
	s_lshl_b64 s[4:5], s[54:55], 2
	s_add_u32 s4, s38, s4
	s_addc_u32 s5, s39, s5
	v_mov_b64_e32 v[6:7], s[4:5]
	flat_atomic_add v6, v[6:7], v215 sc0
	v_cvt_f32_u32_e32 v5, v4
	v_sub_u32_e32 v7, 0, v4
	v_rcp_iflag_f32_e32 v5, v5
	s_nop 0
	v_mul_f32_e32 v5, 0x4f7ffffe, v5
	v_cvt_u32_f32_e32 v5, v5
	v_mul_lo_u32 v7, v7, v5
	v_mul_hi_u32 v7, v5, v7
	v_add_u32_e32 v5, v5, v7
	s_waitcnt vmcnt(0) lgkmcnt(0)
	v_mul_hi_u32 v5, v6, v5
	v_mul_lo_u32 v7, v5, v4
	v_sub_u32_e32 v7, v6, v7
	v_cmp_ge_u32_e32 vcc, v7, v4
	v_add_u32_e32 v8, 1, v5
	s_nop 0
	v_cndmask_b32_e32 v5, v5, v8, vcc
	v_sub_u32_e32 v8, v7, v4
	v_cndmask_b32_e32 v7, v7, v8, vcc
	v_cmp_ge_u32_e32 vcc, v7, v4
	v_add_u32_e32 v7, 1, v5
	v_add_u32_e32 v8, 1, v6
	v_cndmask_b32_e32 v5, v5, v7, vcc
	v_mad_u64_u32 v[6:7], s[4:5], v4, v5, v[4:5]
	v_cmp_ne_u32_e32 vcc, v8, v6
	s_and_saveexec_b64 s[4:5], vcc
	s_xor_b64 s[4:5], exec, s[4:5]
	s_cbranch_execz .LBB0_822
	v_and_b32_e32 v2, 15, v8
	v_cmp_ne_u32_e32 vcc, 0, v2
	s_cbranch_vccnz .Lewb_1
	buffer_wbl2 sc1
.Lewb_1:
	s_add_i32 s54, s26, 0x900
	s_lshl_b64 s[6:7], s[54:55], 2
	s_add_u32 s8, s38, s6
	s_addc_u32 s9, s39, s7
	v_mov_b64_e32 v[6:7], s[8:9]
	flat_load_dword v2, v[6:7] sc1
	s_waitcnt vmcnt(0) lgkmcnt(0)
	v_cmp_eq_u32_e32 vcc, v2, v5
	s_and_saveexec_b64 s[6:7], vcc
	s_cbranch_execz .LBB0_821
	s_mov_b32 s27, 1
	s_mov_b64 s[10:11], 0
	s_branch .LBB0_813

.LBB0_906:
	s_lshl_b32 s26, s38, 6
	s_add_i32 s54, s26, 0x500
	s_lshl_b64 s[4:5], s[54:55], 2
	s_add_u32 s4, s2, s4
	s_addc_u32 s5, s3, s5
	v_mov_b64_e32 v[6:7], s[4:5]
	flat_atomic_add v6, v[6:7], v215 sc0
	v_cvt_f32_u32_e32 v5, v4
	v_sub_u32_e32 v7, 0, v4
	v_rcp_iflag_f32_e32 v5, v5
	s_nop 0
	v_mul_f32_e32 v5, 0x4f7ffffe, v5
	v_cvt_u32_f32_e32 v5, v5
	v_mul_lo_u32 v7, v7, v5
	v_mul_hi_u32 v7, v5, v7
	v_add_u32_e32 v5, v5, v7
	s_waitcnt vmcnt(0) lgkmcnt(0)
	v_mul_hi_u32 v5, v6, v5
	v_mul_lo_u32 v7, v5, v4
	v_sub_u32_e32 v7, v6, v7
	v_cmp_ge_u32_e32 vcc, v7, v4
	v_add_u32_e32 v8, 1, v5
	s_nop 0
	v_cndmask_b32_e32 v5, v5, v8, vcc
	v_sub_u32_e32 v8, v7, v4
	v_cndmask_b32_e32 v7, v7, v8, vcc
	v_cmp_ge_u32_e32 vcc, v7, v4
	v_add_u32_e32 v7, 1, v5
	v_add_u32_e32 v8, 1, v6
	v_cndmask_b32_e32 v5, v5, v7, vcc
	v_mad_u64_u32 v[6:7], s[4:5], v4, v5, v[4:5]
	v_cmp_ne_u32_e32 vcc, v8, v6
	s_and_saveexec_b64 s[4:5], vcc
	s_xor_b64 s[4:5], exec, s[4:5]
	s_cbranch_execz .LBB0_919
	v_and_b32_e32 v2, 15, v8
	v_cmp_ne_u32_e32 vcc, 0, v2
	s_cbranch_vccnz .Lewb_2
	buffer_wbl2 sc1
.Lewb_2:
	s_add_i32 s54, s26, 0x900
	s_lshl_b64 s[6:7], s[54:55], 2
	s_add_u32 s8, s2, s6
	s_addc_u32 s9, s3, s7
	v_mov_b64_e32 v[6:7], s[8:9]
	flat_load_dword v2, v[6:7] sc1
	s_waitcnt vmcnt(0) lgkmcnt(0)
	v_cmp_eq_u32_e32 vcc, v2, v5
	s_and_saveexec_b64 s[6:7], vcc
	s_cbranch_execz .LBB0_918
	s_mov_b32 s27, 1
	s_mov_b64 s[10:11], 0
	s_branch .LBB0_910

.LBB0_1610:
	s_lshl_b32 s24, s36, 6
	s_add_i32 s54, s24, 0x500
	s_lshl_b64 s[0:1], s[54:55], 2
	s_add_u32 s0, s20, s0
	s_addc_u32 s1, s21, s1
	v_mov_b64_e32 v[6:7], s[0:1]
	flat_atomic_add v6, v[6:7], v215 sc0
	v_cvt_f32_u32_e32 v5, v4
	v_sub_u32_e32 v7, 0, v4
	v_rcp_iflag_f32_e32 v5, v5
	s_nop 0
	v_mul_f32_e32 v5, 0x4f7ffffe, v5
	v_cvt_u32_f32_e32 v5, v5
	v_mul_lo_u32 v7, v7, v5
	v_mul_hi_u32 v7, v5, v7
	v_add_u32_e32 v5, v5, v7
	s_waitcnt vmcnt(0) lgkmcnt(0)
	v_mul_hi_u32 v5, v6, v5
	v_mul_lo_u32 v7, v5, v4
	v_sub_u32_e32 v7, v6, v7
	v_cmp_ge_u32_e32 vcc, v7, v4
	v_add_u32_e32 v8, 1, v5
	s_nop 0
	v_cndmask_b32_e32 v5, v5, v8, vcc
	v_sub_u32_e32 v8, v7, v4
	v_cndmask_b32_e32 v7, v7, v8, vcc
	v_cmp_ge_u32_e32 vcc, v7, v4
	v_add_u32_e32 v7, 1, v5
	v_add_u32_e32 v8, 1, v6
	v_cndmask_b32_e32 v5, v5, v7, vcc
	v_mad_u64_u32 v[6:7], s[0:1], v4, v5, v[4:5]
	v_cmp_ne_u32_e32 vcc, v8, v6
	s_and_saveexec_b64 s[0:1], vcc
	s_xor_b64 s[0:1], exec, s[0:1]
	s_cbranch_execz .LBB0_1623
	v_and_b32_e32 v2, 15, v8
	v_cmp_ne_u32_e32 vcc, 0, v2
	s_cbranch_vccnz .Lewb_6
	buffer_wbl2 sc1
.Lewb_6:
	s_add_i32 s54, s24, 0x900
	s_lshl_b64 s[4:5], s[54:55], 2
	s_add_u32 s6, s20, s4
	s_addc_u32 s7, s21, s5
	v_mov_b64_e32 v[6:7], s[6:7]
	flat_load_dword v2, v[6:7] sc1
	s_waitcnt vmcnt(0) lgkmcnt(0)
	v_cmp_eq_u32_e32 vcc, v2, v5
	s_and_saveexec_b64 s[4:5], vcc
	s_cbranch_execz .LBB0_1622
	s_mov_b32 s25, 1
	s_mov_b64 s[8:9], 0
	s_branch .LBB0_1614
